# first grid barrier moved from the runtime's cooperative barrier object to a flag-guarded counter in d_ws; compute_mod silu fill with all loads in flight
# speedup vs baseline: 1.0455x; 1.0094x over previous
; DI int oidx(int i) { asm volatile("" : "+s"(i)); return i; }
; DN void compute_mod(const Params& p, char* smem) {
;     ...
;       for (int i = tid; i < 17 * 256; i += 256) {
;         int r = i >> 8, k = i & 255;
;         float c = (r < 16) ? p.in[oidx(1)][r * DM + kc * 256 + k] : p.in[oidx(3)][kc * 256 + k];
;         sc[i] = c / (1.f + expf(-c));
;       }
.LBB0_51:
	s_or_b64 exec, exec, s[8:9]
	s_and_saveexec_b64 s[14:15], s[4:5]
	s_cbranch_execz .LBB0_58
	v_lshl_or_b32 v76, s26, 8, v121
	s_load_dwordx2 s[28:29], s[0:1], 0x8
	s_load_dwordx2 s[16:17], s[0:1], 0x18
	v_lshlrev_b32_e32 v9, 2, v76
	s_waitcnt lgkmcnt(0)
	global_load_dword v52, v9, s[28:29]
	s_add_u32 s28, s28, 0x1000
	s_addc_u32 s29, s29, 0
	global_load_dword v53, v9, s[28:29]
	s_add_u32 s28, s28, 0x1000
	s_addc_u32 s29, s29, 0
	global_load_dword v54, v9, s[28:29]
	s_add_u32 s28, s28, 0x1000
	s_addc_u32 s29, s29, 0
	global_load_dword v55, v9, s[28:29]
	s_add_u32 s28, s28, 0x1000
	s_addc_u32 s29, s29, 0
	global_load_dword v56, v9, s[28:29]
	s_add_u32 s28, s28, 0x1000
	s_addc_u32 s29, s29, 0
	global_load_dword v57, v9, s[28:29]
	s_add_u32 s28, s28, 0x1000
	s_addc_u32 s29, s29, 0
	global_load_dword v58, v9, s[28:29]
	s_add_u32 s28, s28, 0x1000
	s_addc_u32 s29, s29, 0
	global_load_dword v59, v9, s[28:29]
	s_add_u32 s28, s28, 0x1000
	s_addc_u32 s29, s29, 0
	global_load_dword v60, v9, s[28:29]
	s_add_u32 s28, s28, 0x1000
	s_addc_u32 s29, s29, 0
	global_load_dword v61, v9, s[28:29]
	s_add_u32 s28, s28, 0x1000
	s_addc_u32 s29, s29, 0
	global_load_dword v62, v9, s[28:29]
	s_add_u32 s28, s28, 0x1000
	s_addc_u32 s29, s29, 0
	global_load_dword v63, v9, s[28:29]
	s_add_u32 s28, s28, 0x1000
	s_addc_u32 s29, s29, 0
	global_load_dword v64, v9, s[28:29]
	s_add_u32 s28, s28, 0x1000
	s_addc_u32 s29, s29, 0
	global_load_dword v65, v9, s[28:29]
	s_add_u32 s28, s28, 0x1000
	s_addc_u32 s29, s29, 0
	global_load_dword v66, v9, s[28:29]
	s_add_u32 s28, s28, 0x1000
	s_addc_u32 s29, s29, 0
	global_load_dword v67, v9, s[28:29]
	global_load_dword v68, v9, s[16:17]
	s_waitcnt vmcnt(16)
	v_mul_f32_e32 v5, 0xbfb8aa3b, v52
	v_rndne_f32_e32 v8, v5
	v_fma_f32 v9, v52, s20, -v5
	v_sub_f32_e32 v5, v5, v8
	v_fmac_f32_e32 v9, 0xb2a5705f, v52
	v_add_f32_e32 v5, v5, v9
	v_cvt_i32_f32_e32 v8, v8
	v_exp_f32_e32 v5, v5
	v_cmp_nlt_f32_e64 s[8:9], s21, v52
	s_nop 0
	v_ldexp_f32 v5, v5, v8
	v_cndmask_b32_e64 v5, 0, v5, s[8:9]
	v_cmp_ngt_f32_e64 s[8:9], s22, v52
	s_nop 1
	v_cndmask_b32_e64 v5, v127, v5, s[8:9]
	v_add_f32_e32 v5, 1.0, v5
	v_div_scale_f32 v7, s[8:9], v5, v5, v52
	v_rcp_f32_e32 v8, v7
	v_div_scale_f32 v10, vcc, v52, v5, v52
	v_fma_f32 v11, -v7, v8, 1.0
	v_fmac_f32_e32 v8, v11, v8
	v_mul_f32_e32 v11, v10, v8
	v_fma_f32 v14, -v7, v11, v10
	v_fmac_f32_e32 v11, v14, v8
	v_fma_f32 v7, -v7, v11, v10
	v_div_fmas_f32 v7, v7, v8, v11
	v_div_fixup_f32 v4, v7, v5, v52
	ds_write_b32 v124, v4
	s_waitcnt vmcnt(15)
	v_mul_f32_e32 v5, 0xbfb8aa3b, v53
	v_rndne_f32_e32 v8, v5
	v_fma_f32 v9, v53, s20, -v5
	v_sub_f32_e32 v5, v5, v8
	v_fmac_f32_e32 v9, 0xb2a5705f, v53
	v_add_f32_e32 v5, v5, v9
	v_cvt_i32_f32_e32 v8, v8
	v_exp_f32_e32 v5, v5
	v_cmp_nlt_f32_e64 s[8:9], s21, v53
	s_nop 0
	v_ldexp_f32 v5, v5, v8
	v_cndmask_b32_e64 v5, 0, v5, s[8:9]
	v_cmp_ngt_f32_e64 s[8:9], s22, v53
	s_nop 1
	v_cndmask_b32_e64 v5, v127, v5, s[8:9]
	v_add_f32_e32 v5, 1.0, v5
	v_div_scale_f32 v7, s[8:9], v5, v5, v53
	v_rcp_f32_e32 v8, v7
	v_div_scale_f32 v10, vcc, v53, v5, v53
	v_fma_f32 v11, -v7, v8, 1.0
	v_fmac_f32_e32 v8, v11, v8
	v_mul_f32_e32 v11, v10, v8
	v_fma_f32 v14, -v7, v11, v10
	v_fmac_f32_e32 v11, v14, v8
	v_fma_f32 v7, -v7, v11, v10
	v_div_fmas_f32 v7, v7, v8, v11
	v_div_fixup_f32 v4, v7, v5, v53
	ds_write_b32 v124, v4 offset:1024
	s_waitcnt vmcnt(14)
	v_mul_f32_e32 v5, 0xbfb8aa3b, v54
	v_rndne_f32_e32 v8, v5
	v_fma_f32 v9, v54, s20, -v5
	v_sub_f32_e32 v5, v5, v8
	v_fmac_f32_e32 v9, 0xb2a5705f, v54
	v_add_f32_e32 v5, v5, v9
	v_cvt_i32_f32_e32 v8, v8
	v_exp_f32_e32 v5, v5
	v_cmp_nlt_f32_e64 s[8:9], s21, v54
	s_nop 0
	v_ldexp_f32 v5, v5, v8
	v_cndmask_b32_e64 v5, 0, v5, s[8:9]
	v_cmp_ngt_f32_e64 s[8:9], s22, v54
	s_nop 1
	v_cndmask_b32_e64 v5, v127, v5, s[8:9]
	v_add_f32_e32 v5, 1.0, v5
	v_div_scale_f32 v7, s[8:9], v5, v5, v54
	v_rcp_f32_e32 v8, v7
	v_div_scale_f32 v10, vcc, v54, v5, v54
	v_fma_f32 v11, -v7, v8, 1.0
	v_fmac_f32_e32 v8, v11, v8
	v_mul_f32_e32 v11, v10, v8
	v_fma_f32 v14, -v7, v11, v10
	v_fmac_f32_e32 v11, v14, v8
	v_fma_f32 v7, -v7, v11, v10
	v_div_fmas_f32 v7, v7, v8, v11
	v_div_fixup_f32 v4, v7, v5, v54
	ds_write_b32 v124, v4 offset:2048
	s_waitcnt vmcnt(13)
	v_mul_f32_e32 v5, 0xbfb8aa3b, v55
	v_rndne_f32_e32 v8, v5
	v_fma_f32 v9, v55, s20, -v5
	v_sub_f32_e32 v5, v5, v8
	v_fmac_f32_e32 v9, 0xb2a5705f, v55
	v_add_f32_e32 v5, v5, v9
	v_cvt_i32_f32_e32 v8, v8
	v_exp_f32_e32 v5, v5
	v_cmp_nlt_f32_e64 s[8:9], s21, v55
	s_nop 0
	v_ldexp_f32 v5, v5, v8
	v_cndmask_b32_e64 v5, 0, v5, s[8:9]
	v_cmp_ngt_f32_e64 s[8:9], s22, v55
	s_nop 1
	v_cndmask_b32_e64 v5, v127, v5, s[8:9]
	v_add_f32_e32 v5, 1.0, v5
	v_div_scale_f32 v7, s[8:9], v5, v5, v55
	v_rcp_f32_e32 v8, v7
	v_div_scale_f32 v10, vcc, v55, v5, v55
	v_fma_f32 v11, -v7, v8, 1.0
	v_fmac_f32_e32 v8, v11, v8
	v_mul_f32_e32 v11, v10, v8
	v_fma_f32 v14, -v7, v11, v10
	v_fmac_f32_e32 v11, v14, v8
	v_fma_f32 v7, -v7, v11, v10
	v_div_fmas_f32 v7, v7, v8, v11
	v_div_fixup_f32 v4, v7, v5, v55
	ds_write_b32 v124, v4 offset:3072
	s_waitcnt vmcnt(12)
	v_mul_f32_e32 v5, 0xbfb8aa3b, v56
	v_rndne_f32_e32 v8, v5
	v_fma_f32 v9, v56, s20, -v5
	v_sub_f32_e32 v5, v5, v8
	v_fmac_f32_e32 v9, 0xb2a5705f, v56
	v_add_f32_e32 v5, v5, v9
	v_cvt_i32_f32_e32 v8, v8
	v_exp_f32_e32 v5, v5
	v_cmp_nlt_f32_e64 s[8:9], s21, v56
	s_nop 0
	v_ldexp_f32 v5, v5, v8
	v_cndmask_b32_e64 v5, 0, v5, s[8:9]
	v_cmp_ngt_f32_e64 s[8:9], s22, v56
	s_nop 1
	v_cndmask_b32_e64 v5, v127, v5, s[8:9]
	v_add_f32_e32 v5, 1.0, v5
	v_div_scale_f32 v7, s[8:9], v5, v5, v56
	v_rcp_f32_e32 v8, v7
	v_div_scale_f32 v10, vcc, v56, v5, v56
	v_fma_f32 v11, -v7, v8, 1.0
	v_fmac_f32_e32 v8, v11, v8
	v_mul_f32_e32 v11, v10, v8
	v_fma_f32 v14, -v7, v11, v10
	v_fmac_f32_e32 v11, v14, v8
	v_fma_f32 v7, -v7, v11, v10
	v_div_fmas_f32 v7, v7, v8, v11
	v_div_fixup_f32 v4, v7, v5, v56
	ds_write_b32 v124, v4 offset:4096
	s_waitcnt vmcnt(11)
; DI int oidx(int i) { asm volatile("" : "+s"(i)); return i; }
; DN void compute_mod(const Params& p, char* smem) {
;     ...
;       for (int i = tid; i < 17 * 256; i += 256) {
;         int r = i >> 8, k = i & 255;
;         float c = (r < 16) ? p.in[oidx(1)][r * DM + kc * 256 + k] : p.in[oidx(3)][kc * 256 + k];
;         sc[i] = c / (1.f + expf(-c));
;       }
	v_mul_f32_e32 v5, 0xbfb8aa3b, v57
	v_rndne_f32_e32 v8, v5
	v_fma_f32 v9, v57, s20, -v5
	v_sub_f32_e32 v5, v5, v8
	v_fmac_f32_e32 v9, 0xb2a5705f, v57
	v_add_f32_e32 v5, v5, v9
	v_cvt_i32_f32_e32 v8, v8
	v_exp_f32_e32 v5, v5
	v_cmp_nlt_f32_e64 s[8:9], s21, v57
	s_nop 0
	v_ldexp_f32 v5, v5, v8
	v_cndmask_b32_e64 v5, 0, v5, s[8:9]
	v_cmp_ngt_f32_e64 s[8:9], s22, v57
	s_nop 1
	v_cndmask_b32_e64 v5, v127, v5, s[8:9]
	v_add_f32_e32 v5, 1.0, v5
	v_div_scale_f32 v7, s[8:9], v5, v5, v57
	v_rcp_f32_e32 v8, v7
	v_div_scale_f32 v10, vcc, v57, v5, v57
	v_fma_f32 v11, -v7, v8, 1.0
	v_fmac_f32_e32 v8, v11, v8
	v_mul_f32_e32 v11, v10, v8
	v_fma_f32 v14, -v7, v11, v10
	v_fmac_f32_e32 v11, v14, v8
	v_fma_f32 v7, -v7, v11, v10
	v_div_fmas_f32 v7, v7, v8, v11
	v_div_fixup_f32 v4, v7, v5, v57
	ds_write_b32 v124, v4 offset:5120
	s_waitcnt vmcnt(10)
	v_mul_f32_e32 v5, 0xbfb8aa3b, v58
	v_rndne_f32_e32 v8, v5
	v_fma_f32 v9, v58, s20, -v5
	v_sub_f32_e32 v5, v5, v8
	v_fmac_f32_e32 v9, 0xb2a5705f, v58
	v_add_f32_e32 v5, v5, v9
	v_cvt_i32_f32_e32 v8, v8
	v_exp_f32_e32 v5, v5
	v_cmp_nlt_f32_e64 s[8:9], s21, v58
	s_nop 0
	v_ldexp_f32 v5, v5, v8
	v_cndmask_b32_e64 v5, 0, v5, s[8:9]
	v_cmp_ngt_f32_e64 s[8:9], s22, v58
	s_nop 1
	v_cndmask_b32_e64 v5, v127, v5, s[8:9]
	v_add_f32_e32 v5, 1.0, v5
	v_div_scale_f32 v7, s[8:9], v5, v5, v58
	v_rcp_f32_e32 v8, v7
	v_div_scale_f32 v10, vcc, v58, v5, v58
	v_fma_f32 v11, -v7, v8, 1.0
	v_fmac_f32_e32 v8, v11, v8
	v_mul_f32_e32 v11, v10, v8
	v_fma_f32 v14, -v7, v11, v10
	v_fmac_f32_e32 v11, v14, v8
	v_fma_f32 v7, -v7, v11, v10
	v_div_fmas_f32 v7, v7, v8, v11
	v_div_fixup_f32 v4, v7, v5, v58
	ds_write_b32 v124, v4 offset:6144
	s_waitcnt vmcnt(9)
	v_mul_f32_e32 v5, 0xbfb8aa3b, v59
	v_rndne_f32_e32 v8, v5
	v_fma_f32 v9, v59, s20, -v5
	v_sub_f32_e32 v5, v5, v8
	v_fmac_f32_e32 v9, 0xb2a5705f, v59
	v_add_f32_e32 v5, v5, v9
	v_cvt_i32_f32_e32 v8, v8
	v_exp_f32_e32 v5, v5
	v_cmp_nlt_f32_e64 s[8:9], s21, v59
	s_nop 0
	v_ldexp_f32 v5, v5, v8
	v_cndmask_b32_e64 v5, 0, v5, s[8:9]
	v_cmp_ngt_f32_e64 s[8:9], s22, v59
	s_nop 1
	v_cndmask_b32_e64 v5, v127, v5, s[8:9]
	v_add_f32_e32 v5, 1.0, v5
	v_div_scale_f32 v7, s[8:9], v5, v5, v59
	v_rcp_f32_e32 v8, v7
	v_div_scale_f32 v10, vcc, v59, v5, v59
	v_fma_f32 v11, -v7, v8, 1.0
	v_fmac_f32_e32 v8, v11, v8
	v_mul_f32_e32 v11, v10, v8
	v_fma_f32 v14, -v7, v11, v10
	v_fmac_f32_e32 v11, v14, v8
	v_fma_f32 v7, -v7, v11, v10
	v_div_fmas_f32 v7, v7, v8, v11
	v_div_fixup_f32 v4, v7, v5, v59
	ds_write_b32 v124, v4 offset:7168
	s_waitcnt vmcnt(8)
	v_mul_f32_e32 v5, 0xbfb8aa3b, v60
	v_rndne_f32_e32 v8, v5
	v_fma_f32 v9, v60, s20, -v5
	v_sub_f32_e32 v5, v5, v8
	v_fmac_f32_e32 v9, 0xb2a5705f, v60
	v_add_f32_e32 v5, v5, v9
	v_cvt_i32_f32_e32 v8, v8
	v_exp_f32_e32 v5, v5
	v_cmp_nlt_f32_e64 s[8:9], s21, v60
	s_nop 0
	v_ldexp_f32 v5, v5, v8
	v_cndmask_b32_e64 v5, 0, v5, s[8:9]
	v_cmp_ngt_f32_e64 s[8:9], s22, v60
	s_nop 1
	v_cndmask_b32_e64 v5, v127, v5, s[8:9]
	v_add_f32_e32 v5, 1.0, v5
	v_div_scale_f32 v7, s[8:9], v5, v5, v60
	v_rcp_f32_e32 v8, v7
	v_div_scale_f32 v10, vcc, v60, v5, v60
	v_fma_f32 v11, -v7, v8, 1.0
	v_fmac_f32_e32 v8, v11, v8
	v_mul_f32_e32 v11, v10, v8
	v_fma_f32 v14, -v7, v11, v10
	v_fmac_f32_e32 v11, v14, v8
	v_fma_f32 v7, -v7, v11, v10
	v_div_fmas_f32 v7, v7, v8, v11
	v_div_fixup_f32 v4, v7, v5, v60
	ds_write_b32 v124, v4 offset:8192
	s_waitcnt vmcnt(7)
	v_mul_f32_e32 v5, 0xbfb8aa3b, v61
	v_rndne_f32_e32 v8, v5
	v_fma_f32 v9, v61, s20, -v5
	v_sub_f32_e32 v5, v5, v8
	v_fmac_f32_e32 v9, 0xb2a5705f, v61
	v_add_f32_e32 v5, v5, v9
	v_cvt_i32_f32_e32 v8, v8
	v_exp_f32_e32 v5, v5
	v_cmp_nlt_f32_e64 s[8:9], s21, v61
	s_nop 0
	v_ldexp_f32 v5, v5, v8
	v_cndmask_b32_e64 v5, 0, v5, s[8:9]
	v_cmp_ngt_f32_e64 s[8:9], s22, v61
	s_nop 1
	v_cndmask_b32_e64 v5, v127, v5, s[8:9]
	v_add_f32_e32 v5, 1.0, v5
	v_div_scale_f32 v7, s[8:9], v5, v5, v61
	v_rcp_f32_e32 v8, v7
	v_div_scale_f32 v10, vcc, v61, v5, v61
	v_fma_f32 v11, -v7, v8, 1.0
	v_fmac_f32_e32 v8, v11, v8
	v_mul_f32_e32 v11, v10, v8
	v_fma_f32 v14, -v7, v11, v10
	v_fmac_f32_e32 v11, v14, v8
	v_fma_f32 v7, -v7, v11, v10
	v_div_fmas_f32 v7, v7, v8, v11
	v_div_fixup_f32 v4, v7, v5, v61
	ds_write_b32 v124, v4 offset:9216
	s_waitcnt vmcnt(6)
	v_mul_f32_e32 v5, 0xbfb8aa3b, v62
	v_rndne_f32_e32 v8, v5
	v_fma_f32 v9, v62, s20, -v5
	v_sub_f32_e32 v5, v5, v8
	v_fmac_f32_e32 v9, 0xb2a5705f, v62
	v_add_f32_e32 v5, v5, v9
	v_cvt_i32_f32_e32 v8, v8
	v_exp_f32_e32 v5, v5
	v_cmp_nlt_f32_e64 s[8:9], s21, v62
	s_nop 0
	v_ldexp_f32 v5, v5, v8
	v_cndmask_b32_e64 v5, 0, v5, s[8:9]
	v_cmp_ngt_f32_e64 s[8:9], s22, v62
	s_nop 1
	v_cndmask_b32_e64 v5, v127, v5, s[8:9]
	v_add_f32_e32 v5, 1.0, v5
	v_div_scale_f32 v7, s[8:9], v5, v5, v62
	v_rcp_f32_e32 v8, v7
	v_div_scale_f32 v10, vcc, v62, v5, v62
	v_fma_f32 v11, -v7, v8, 1.0
	v_fmac_f32_e32 v8, v11, v8
	v_mul_f32_e32 v11, v10, v8
	v_fma_f32 v14, -v7, v11, v10
	v_fmac_f32_e32 v11, v14, v8
	v_fma_f32 v7, -v7, v11, v10
	v_div_fmas_f32 v7, v7, v8, v11
	v_div_fixup_f32 v4, v7, v5, v62
	ds_write_b32 v124, v4 offset:10240
	s_waitcnt vmcnt(5)
; DI int oidx(int i) { asm volatile("" : "+s"(i)); return i; }
; DN void compute_mod(const Params& p, char* smem) {
;     ...
;       for (int i = tid; i < 17 * 256; i += 256) {
;         int r = i >> 8, k = i & 255;
;         float c = (r < 16) ? p.in[oidx(1)][r * DM + kc * 256 + k] : p.in[oidx(3)][kc * 256 + k];
;         sc[i] = c / (1.f + expf(-c));
;       }
	v_mul_f32_e32 v5, 0xbfb8aa3b, v63
	v_rndne_f32_e32 v8, v5
	v_fma_f32 v9, v63, s20, -v5
	v_sub_f32_e32 v5, v5, v8
	v_fmac_f32_e32 v9, 0xb2a5705f, v63
	v_add_f32_e32 v5, v5, v9
	v_cvt_i32_f32_e32 v8, v8
	v_exp_f32_e32 v5, v5
	v_cmp_nlt_f32_e64 s[8:9], s21, v63
	s_nop 0
	v_ldexp_f32 v5, v5, v8
	v_cndmask_b32_e64 v5, 0, v5, s[8:9]
	v_cmp_ngt_f32_e64 s[8:9], s22, v63
	s_nop 1
	v_cndmask_b32_e64 v5, v127, v5, s[8:9]
	v_add_f32_e32 v5, 1.0, v5
	v_div_scale_f32 v7, s[8:9], v5, v5, v63
	v_rcp_f32_e32 v8, v7
	v_div_scale_f32 v10, vcc, v63, v5, v63
	v_fma_f32 v11, -v7, v8, 1.0
	v_fmac_f32_e32 v8, v11, v8
	v_mul_f32_e32 v11, v10, v8
	v_fma_f32 v14, -v7, v11, v10
	v_fmac_f32_e32 v11, v14, v8
	v_fma_f32 v7, -v7, v11, v10
	v_div_fmas_f32 v7, v7, v8, v11
	v_div_fixup_f32 v4, v7, v5, v63
	ds_write_b32 v124, v4 offset:11264
	s_waitcnt vmcnt(4)
	v_mul_f32_e32 v5, 0xbfb8aa3b, v64
	v_rndne_f32_e32 v8, v5
	v_fma_f32 v9, v64, s20, -v5
	v_sub_f32_e32 v5, v5, v8
	v_fmac_f32_e32 v9, 0xb2a5705f, v64
	v_add_f32_e32 v5, v5, v9
	v_cvt_i32_f32_e32 v8, v8
	v_exp_f32_e32 v5, v5
	v_cmp_nlt_f32_e64 s[8:9], s21, v64
	s_nop 0
	v_ldexp_f32 v5, v5, v8
	v_cndmask_b32_e64 v5, 0, v5, s[8:9]
	v_cmp_ngt_f32_e64 s[8:9], s22, v64
	s_nop 1
	v_cndmask_b32_e64 v5, v127, v5, s[8:9]
	v_add_f32_e32 v5, 1.0, v5
	v_div_scale_f32 v7, s[8:9], v5, v5, v64
	v_rcp_f32_e32 v8, v7
	v_div_scale_f32 v10, vcc, v64, v5, v64
	v_fma_f32 v11, -v7, v8, 1.0
	v_fmac_f32_e32 v8, v11, v8
	v_mul_f32_e32 v11, v10, v8
	v_fma_f32 v14, -v7, v11, v10
	v_fmac_f32_e32 v11, v14, v8
	v_fma_f32 v7, -v7, v11, v10
	v_div_fmas_f32 v7, v7, v8, v11
	v_div_fixup_f32 v4, v7, v5, v64
	ds_write_b32 v124, v4 offset:12288
	s_waitcnt vmcnt(3)
	v_mul_f32_e32 v5, 0xbfb8aa3b, v65
	v_rndne_f32_e32 v8, v5
	v_fma_f32 v9, v65, s20, -v5
	v_sub_f32_e32 v5, v5, v8
	v_fmac_f32_e32 v9, 0xb2a5705f, v65
	v_add_f32_e32 v5, v5, v9
	v_cvt_i32_f32_e32 v8, v8
	v_exp_f32_e32 v5, v5
	v_cmp_nlt_f32_e64 s[8:9], s21, v65
	s_nop 0
	v_ldexp_f32 v5, v5, v8
	v_cndmask_b32_e64 v5, 0, v5, s[8:9]
	v_cmp_ngt_f32_e64 s[8:9], s22, v65
	s_nop 1
	v_cndmask_b32_e64 v5, v127, v5, s[8:9]
	v_add_f32_e32 v5, 1.0, v5
	v_div_scale_f32 v7, s[8:9], v5, v5, v65
	v_rcp_f32_e32 v8, v7
	v_div_scale_f32 v10, vcc, v65, v5, v65
	v_fma_f32 v11, -v7, v8, 1.0
	v_fmac_f32_e32 v8, v11, v8
	v_mul_f32_e32 v11, v10, v8
	v_fma_f32 v14, -v7, v11, v10
	v_fmac_f32_e32 v11, v14, v8
	v_fma_f32 v7, -v7, v11, v10
	v_div_fmas_f32 v7, v7, v8, v11
	v_div_fixup_f32 v4, v7, v5, v65
	ds_write_b32 v124, v4 offset:13312
	s_waitcnt vmcnt(2)
	v_mul_f32_e32 v5, 0xbfb8aa3b, v66
	v_rndne_f32_e32 v8, v5
	v_fma_f32 v9, v66, s20, -v5
	v_sub_f32_e32 v5, v5, v8
	v_fmac_f32_e32 v9, 0xb2a5705f, v66
	v_add_f32_e32 v5, v5, v9
	v_cvt_i32_f32_e32 v8, v8
	v_exp_f32_e32 v5, v5
	v_cmp_nlt_f32_e64 s[8:9], s21, v66
	s_nop 0
	v_ldexp_f32 v5, v5, v8
	v_cndmask_b32_e64 v5, 0, v5, s[8:9]
	v_cmp_ngt_f32_e64 s[8:9], s22, v66
	s_nop 1
	v_cndmask_b32_e64 v5, v127, v5, s[8:9]
	v_add_f32_e32 v5, 1.0, v5
	v_div_scale_f32 v7, s[8:9], v5, v5, v66
	v_rcp_f32_e32 v8, v7
	v_div_scale_f32 v10, vcc, v66, v5, v66
	v_fma_f32 v11, -v7, v8, 1.0
	v_fmac_f32_e32 v8, v11, v8
	v_mul_f32_e32 v11, v10, v8
	v_fma_f32 v14, -v7, v11, v10
	v_fmac_f32_e32 v11, v14, v8
	v_fma_f32 v7, -v7, v11, v10
	v_div_fmas_f32 v7, v7, v8, v11
	v_div_fixup_f32 v4, v7, v5, v66
	ds_write_b32 v124, v4 offset:14336
	s_waitcnt vmcnt(1)
	v_mul_f32_e32 v5, 0xbfb8aa3b, v67
	v_rndne_f32_e32 v8, v5
	v_fma_f32 v9, v67, s20, -v5
	v_sub_f32_e32 v5, v5, v8
	v_fmac_f32_e32 v9, 0xb2a5705f, v67
	v_add_f32_e32 v5, v5, v9
	v_cvt_i32_f32_e32 v8, v8
	v_exp_f32_e32 v5, v5
	v_cmp_nlt_f32_e64 s[8:9], s21, v67
	s_nop 0
	v_ldexp_f32 v5, v5, v8
	v_cndmask_b32_e64 v5, 0, v5, s[8:9]
	v_cmp_ngt_f32_e64 s[8:9], s22, v67
	s_nop 1
	v_cndmask_b32_e64 v5, v127, v5, s[8:9]
	v_add_f32_e32 v5, 1.0, v5
	v_div_scale_f32 v7, s[8:9], v5, v5, v67
	v_rcp_f32_e32 v8, v7
	v_div_scale_f32 v10, vcc, v67, v5, v67
	v_fma_f32 v11, -v7, v8, 1.0
	v_fmac_f32_e32 v8, v11, v8
	v_mul_f32_e32 v11, v10, v8
	v_fma_f32 v14, -v7, v11, v10
	v_fmac_f32_e32 v11, v14, v8
	v_fma_f32 v7, -v7, v11, v10
	v_div_fmas_f32 v7, v7, v8, v11
	v_div_fixup_f32 v4, v7, v5, v67
	ds_write_b32 v124, v4 offset:15360
	s_waitcnt vmcnt(0)
	v_mul_f32_e32 v5, 0xbfb8aa3b, v68
	v_rndne_f32_e32 v8, v5
	v_fma_f32 v9, v68, s20, -v5
	v_sub_f32_e32 v5, v5, v8
	v_fmac_f32_e32 v9, 0xb2a5705f, v68
	v_add_f32_e32 v5, v5, v9
	v_cvt_i32_f32_e32 v8, v8
	v_exp_f32_e32 v5, v5
	v_cmp_nlt_f32_e64 s[8:9], s21, v68
	s_nop 0
	v_ldexp_f32 v5, v5, v8
	v_cndmask_b32_e64 v5, 0, v5, s[8:9]
	v_cmp_ngt_f32_e64 s[8:9], s22, v68
	s_nop 1
	v_cndmask_b32_e64 v5, v127, v5, s[8:9]
	v_add_f32_e32 v5, 1.0, v5
	v_div_scale_f32 v7, s[8:9], v5, v5, v68
	v_rcp_f32_e32 v8, v7
	v_div_scale_f32 v10, vcc, v68, v5, v68
	v_fma_f32 v11, -v7, v8, 1.0
	v_fmac_f32_e32 v8, v11, v8
	v_mul_f32_e32 v11, v10, v8
	v_fma_f32 v14, -v7, v11, v10
	v_fmac_f32_e32 v11, v14, v8
	v_fma_f32 v7, -v7, v11, v10
	v_div_fmas_f32 v7, v7, v8, v11
	v_div_fixup_f32 v4, v7, v5, v68
	ds_write_b32 v124, v4 offset:16384

; __global__ void __launch_bounds__(512, 2) fwd_megakernel(Params p) {
;     ...
;   if (blockIdx.x == 0 && threadIdx.x < 24) ctr[threadIdx.x] = 0u;
;   if (blockIdx.x == 0 && threadIdx.x == 32) ctr[32] = 0u;
;   grid.sync();
.LBB0_95:
	s_or_b64 exec, exec, s[2:3]
	v_cmp_eq_u32_e32 vcc, 32, v182
	s_and_saveexec_b64 s[2:3], vcc
	s_cbranch_execz .LBB0_97
	s_load_dwordx2 s[4:5], s[0:1], 0x108
	v_mov_b32_e32 v2, 0x2b7c000
	v_mov_b32_e32 v3, 0
	s_waitcnt lgkmcnt(0)
	global_store_dword v2, v3, s[4:5] offset:128
	global_store_dword v2, v3, s[4:5] offset:136
	s_waitcnt vmcnt(0)
	buffer_wbl2 sc1
	s_waitcnt vmcnt(0)
	v_mov_b32_e32 v3, 0x5ca1ab1e
	global_store_dword v2, v3, s[4:5] offset:132 sc0 sc1
	s_waitcnt vmcnt(0)
	buffer_wbl2 sc1
	s_waitcnt vmcnt(0)

; __global__ void __launch_bounds__(512, 2) fwd_megakernel(Params p) {
;     ...
;   grid.sync();
.LBB0_98:
	v_lshrrev_b32_e32 v2, 20, v0
	v_lshrrev_b32_e32 v0, 10, v0
	v_or_b32_e32 v0, v0, v2
	s_movk_i32 s2, 0x3ff
	v_and_or_b32 v0, v0, s2, v182
	v_cmp_eq_u32_e32 vcc, 0, v0
	s_barrier
	s_and_saveexec_b64 s[2:3], vcc
	s_cbranch_execz .LBB0_108
	buffer_wbl2 sc1
	s_waitcnt vmcnt(0)
	s_load_dwordx2 s[4:5], s[0:1], 0x108
	s_load_dword s6, s[0:1], 0x110
	v_mov_b32_e32 v2, 0x2b7c000
	s_waitcnt lgkmcnt(0)
.Lfs_flag:
	global_load_dword v3, v2, s[4:5] offset:132 sc1
	s_waitcnt vmcnt(0)
	v_cmp_ne_u32_e32 vcc, 0x5ca1ab1e, v3
	s_cbranch_vccz .Lfs_go
	s_sleep 1
	s_branch .Lfs_flag
.Lfs_go:
	v_mov_b32_e32 v3, 1
	global_atomic_add v2, v3, s[4:5] offset:136
.Lfs_poll:
	global_load_dword v3, v2, s[4:5] offset:136 sc1
	s_waitcnt vmcnt(0)
	v_cmp_gt_u32_e32 vcc, s6, v3
	s_cbranch_vccz .LBB0_107
	s_sleep 1
	s_branch .Lfs_poll
.LBB0_107:
	buffer_inv sc1
	s_waitcnt vmcnt(0)
; #define LAS __attribute__((address_space(3)))
; DI int oidx(int i) { asm volatile("" : "+s"(i)); return i; }
;   DI bool next(int i, pg8::Unit& u) const {
;     const long L = (long)i * G + c; if (L >= nwg) return false;
;     int wgid = (int)L; { const int q = nwg / pg8::NXCD, r = nwg % pg8::NXCD, xcd = wgid % pg8::NXCD, off = wgid / pg8::NXCD; wgid = (xcd < r ? xcd * (q + 1) : r * (q + 1) + (xcd - r) * q) + off; }
;     const int nig = pg8::WGM * nN, gid = wgid / nig, fm = gid * pg8::WGM, gsz = (nM - fm) < pg8::WGM ? (nM - fm) : pg8::WGM;
;     const int pm = fm + ((wgid % nig) % gsz); u.pn = (wgid % nig) / gsz;
;     u.pm = skip ? (pm >> 3) * 9 + (pm & 7) : pm;
;     u.kofs = lora ? ((u.pn < 4) ? (u.pn >> 1) * 128 : 256) : 0;
;     return true;
;   }
; DN void phase_lora(const Params& p, int l) {
;   pg8::Gemm g; g.A = (const bfr*)(p.ws + OFF_HO); g.Bt = (const bfr*)(p.ws + OFF_WLORA); g.M = MR; g.N = 1280; { int kk_ = 384; asm volatile("" : "+s"(kk_)); g.K = kk_; }
;   MySched S; S.init(144, 5, gridDim.x, blockIdx.x, false); S.lora = true;
;   { int nt_ = 2; asm volatile("" : "+s"(nt_)); g.ntov = nt_; }
;   EpiLora E; E.RW = (bfr*)(p.ws + OFF_RWIN); E.w0 = p.in[oidx(11)] + (size_t)l * 512; E.a0 = p.in[oidx(13)] + (size_t)l * 512;
;   pg8::gemm_phase<EpiLora, MySched, true, true>((LAS unsigned char*)dynlds, g, S, E);
; }
; DN void phase_g1(const Params& p) {
;   pg8::Gemm g; g.A = (const bfr*)(p.ws + OFF_HO); g.Bt = (const bfr*)(p.ws + OFF_WIN); g.M = MR; g.N = NINP; g.K = DM;
;   MySched S; S.init(144, 13, gridDim.x, blockIdx.x, false);
;   EpiP E; E.P = (bfr*)(p.ws + OFF_P);
;   pg8::gemm_phase<EpiP, MySched, true, true>((LAS unsigned char*)dynlds, g, S, E);
; }
.LBB0_108:
	s_or_b64 exec, exec, s[2:3]
	s_barrier
	s_load_dwordx4 s[8:11], s[0:1], 0x100
	s_mov_b64 s[2:3], src_shared_base
	v_writelane_b32 v252, s2, 3
	v_and_b32_e32 v0, 12, v79
	s_waitcnt lgkmcnt(0)
	s_load_dword s8, s[0:1], 0x110
	v_writelane_b32 v252, s3, 4
	s_add_i32 s2, 0, 0x21000
	v_add_u32_e32 v184, s2, v0
	s_add_u32 s2, s10, 0x1380000
	s_addc_u32 s3, s11, 0
	v_writelane_b32 v252, s2, 5
	v_cmp_eq_u32_e64 s[68:69], 0, v182
	v_mbcnt_lo_u32_b32 v0, -1, 0
	v_writelane_b32 v252, s3, 6
	s_add_u32 s2, s10, 0x880000
	s_addc_u32 s3, s11, 0
	v_writelane_b32 v252, s2, 7
	s_movk_i32 s87, 0x80
	v_mov_b32_e32 v185, 1
	v_writelane_b32 v252, s3, 8
	s_add_u32 s2, s10, 0x680000
	s_addc_u32 s3, s11, 0
	v_writelane_b32 v252, s2, 9
	v_mov_b32_e32 v153, 0
	v_mov_b32_e32 v186, 0x358637bd
	v_writelane_b32 v252, s3, 10
	s_waitcnt lgkmcnt(0)
	s_lshl_b32 s2, s8, 1
	s_add_u32 s12, s10, 0x1900000
	s_addc_u32 s13, s11, 0
	s_lshl_b32 s14, s8, 5
	v_writelane_b32 v252, s2, 11
	s_add_u32 s2, s10, 0x19f0000
	s_addc_u32 s3, s11, 0
	s_add_u32 s16, s10, 0x2b7c100
	v_writelane_b32 v252, s2, 12
	s_addc_u32 s17, s11, 0
	v_mbcnt_hi_u32_b32 v188, -1, v0
	v_writelane_b32 v252, s3, 13
	s_add_u32 s2, s10, 0x1abc000
	s_addc_u32 s3, s11, 0
	v_writelane_b32 v252, s2, 14
	v_mov_b32_e32 v189, 0x1200000
	v_mov_b32_e32 v190, 0xffffff00
	v_writelane_b32 v252, s3, 15
	s_add_u32 s2, s10, 0x2b7c080
	s_addc_u32 s3, s11, 0
	v_writelane_b32 v252, s2, 16
	s_add_u32 s84, s10, 0x737c100
	s_addc_u32 s85, s11, 0
	v_writelane_b32 v252, s3, 17
	v_mov_b32_e32 v191, 0x800
	v_readlane_b32 s9, v252, 0
	s_cmpk_lt_i32 s9, 0x750
	s_cselect_b64 s[2:3], -1, 0
	v_writelane_b32 v252, s2, 18
	v_mov_b32_e32 v187, 0x900
	v_mov_b32_e32 v201, 0x7f800000
	v_writelane_b32 v252, s3, 19
	s_ashr_i32 s2, s9, 31
	v_writelane_b32 v252, s2, 20
	s_lshr_b32 s2, s2, 29
	s_add_i32 s2, s9, s2
	s_ashr_i32 s15, s2, 3
	s_and_b32 s2, s2, -8
	s_sub_i32 s18, s9, s2
	s_cmp_lt_i32 s18, 0
	s_movk_i32 s2, 0xeb
	s_cselect_b32 s2, s2, 0xea
	s_mul_i32 s2, s2, s18
	s_movk_i32 s3, 0x5b
	s_cselect_b32 s3, s3, 0x5a
	s_add_i32 s2, s2, s15
	s_mul_hi_i32 s4, s2, 0x4ec4ec4f
	s_lshr_b32 s5, s4, 31
	s_ashr_i32 s4, s4, 5
	s_add_i32 s4, s4, s5
	s_mul_i32 s5, s4, 0x68
	s_sub_i32 s5, s2, s5
	s_bfe_i32 s2, s5, 0x80000
	s_bfe_u32 s2, s2, 0x3000c
	s_add_i32 s6, s5, s2
	s_bfe_i32 s2, s6, 0x80000
	s_and_b32 s6, s6, 0xf8
	s_sub_i32 s5, s5, s6
	s_lshl_b32 s4, s4, 3
	s_sext_i32_i16 s7, s2
	s_sext_i32_i8 s5, s5
	s_add_i32 s20, s4, s5
	s_ashr_i32 s4, s7, 3
	s_lshr_b32 s2, s7, 3
	v_writelane_b32 v252, s4, 21
	s_ashr_i32 s4, s8, 31
	v_writelane_b32 v252, s4, 22
	s_add_u32 s4, s10, 0x2abc000
	s_addc_u32 s5, s11, 0
	v_writelane_b32 v252, s4, 23
	s_mul_i32 s3, s3, s18
	v_mov_b32_e32 v196, 0x41b17218
	v_writelane_b32 v252, s5, 24
	s_add_u32 s4, s10, 0x158fc100
	s_addc_u32 s5, s11, 0
	v_writelane_b32 v252, s4, 25
	s_cmpk_lt_i32 s9, 0x2d0
	v_mov_b32_e32 v197, 0xb00
	v_writelane_b32 v252, s5, 26
	s_cselect_b64 s[4:5], -1, 0
	v_writelane_b32 v252, s4, 27
	s_add_i32 s3, s3, s15
	v_mov_b32_e32 v198, 0xff
	v_writelane_b32 v252, s5, 28
	s_mul_hi_i32 s4, s3, 0x66666667
	s_lshr_b32 s5, s4, 31
	s_ashr_i32 s4, s4, 4
	s_add_i32 s4, s4, s5
	s_lshl_b32 s5, s4, 3
	s_mul_i32 s4, s4, 40
	s_sub_i32 s3, s3, s4
	s_bfe_i32 s4, s3, 0x80000
	s_bfe_u32 s4, s4, 0x3000c
	s_add_i32 s6, s3, s4
	s_bfe_i32 s4, s6, 0x80000
	s_and_b32 s6, s6, 0xf8
	s_sub_i32 s6, s3, s6
	s_sext_i32_i16 s7, s4
	s_sext_i32_i8 s6, s6
	v_writelane_b32 v252, s15, 29
	s_add_i32 s15, s5, s6
	s_ashr_i32 s5, s7, 3
	v_writelane_b32 v252, s5, 30
	s_lshl_b32 s5, s5, 7
	s_lshr_b32 s4, s7, 3
	s_and_b32 s5, s5, 0xffffff00
	s_cmp_lt_i32 s3, 32
	s_cselect_b32 s5, s5, 0x200
	s_ashr_i32 s8, s5, 31
	s_cmpk_lt_i32 s9, 0x80
	s_cselect_b64 s[6:7], -1, 0
	v_writelane_b32 v252, s6, 31
	v_mov_b32_e32 v199, 0xfffff500
	v_mov_b32_e32 v200, 0x5800
	v_writelane_b32 v252, s7, 32
	s_add_u32 s6, s10, 0x1b2fc100
	s_addc_u32 s7, s11, 0
	v_writelane_b32 v252, s6, 33
	s_mov_b32 s33, 0x800000
	s_movk_i32 s96, 0x1000
	v_writelane_b32 v252, s7, 34
	s_add_u32 s6, s10, 0x2b7c000
	s_addc_u32 s7, s11, 0
	s_add_u32 s94, s10, 0x1d6fc100
	v_writelane_b32 v252, s6, 35
	s_addc_u32 s95, s11, 0
	s_movk_i32 s97, 0x90
	v_writelane_b32 v252, s7, 36
	s_add_u32 s6, s10, 0x1c4fc100
	s_addc_u32 s7, s11, 0
	v_writelane_b32 v252, s6, 37
	s_lshr_b32 s3, s18, 31
	s_ashr_i32 s21, s20, 31
	v_writelane_b32 v252, s7, 38
	v_writelane_b32 v252, s18, 39
	v_writelane_b32 v252, s3, 40
	s_mov_b32 s6, s20
	v_writelane_b32 v252, s6, 41
	s_movk_i32 s88, 0x1980
	s_movk_i32 s89, 0x84
	v_writelane_b32 v252, s7, 42
	s_lshl_b64 s[6:7], s[20:21], 19
	s_add_u32 s6, s16, s6
	s_addc_u32 s7, s17, s7
	s_bfe_i64 s[2:3], s[2:3], 0x100000
	s_lshl_b64 s[2:3], s[2:3], 19
	s_add_u32 s2, s10, s2
	s_addc_u32 s3, s11, s3
	s_add_u32 s18, s2, 0x40000
	s_addc_u32 s19, s3, 0
	v_writelane_b32 v252, s18, 43
	s_movk_i32 s67, 0x420
	s_mov_b64 s[92:93], -1
	v_writelane_b32 v252, s19, 44
	s_add_u32 s18, s6, 0x40000
	v_writelane_b32 v252, s6, 45
	s_addc_u32 s19, s7, 0
	s_mov_b64 s[74:75], 0x1000
	v_writelane_b32 v252, s7, 46
	v_writelane_b32 v252, s18, 47
	s_add_u32 s6, s2, 0x40080
	s_mov_b64 s[78:79], 0x80
	v_writelane_b32 v252, s19, 48
	v_writelane_b32 v252, s2, 49
	s_addc_u32 s7, s3, 0
	s_mov_b32 s81, 0
	v_writelane_b32 v252, s3, 50
	v_writelane_b32 v252, s6, 51
	s_ashr_i32 s2, s15, 31
	s_nop 0
	v_writelane_b32 v252, s7, 52
	v_writelane_b32 v252, s15, 53
	v_writelane_b32 v252, s2, 54
	s_bfe_i64 s[2:3], s[4:5], 0x100000
	v_writelane_b32 v252, s2, 55
	s_nop 1
	v_writelane_b32 v252, s3, 56
	s_add_u32 s2, s12, s5
	v_writelane_b32 v252, s2, 57
	v_writelane_b32 v252, s12, 58
	s_addc_u32 s2, s13, s8
	s_nop 0
	v_writelane_b32 v252, s13, 59
	v_writelane_b32 v252, s2, 60
	s_add_u32 s2, s16, s5
	v_writelane_b32 v252, s2, 61
	v_writelane_b32 v252, s16, 62
	s_addc_u32 s2, s17, s8
	v_writelane_b32 v253, s2, 0
	s_mov_b32 s2, s42
	s_ashr_i32 s43, s42, 31
	v_writelane_b32 v253, s2, 1
	s_ashr_i32 s15, s14, 31
	v_writelane_b32 v252, s17, 63
	v_writelane_b32 v253, s3, 2
	s_lshl_b64 s[2:3], s[42:43], 1
	v_writelane_b32 v253, s2, 3
	s_mov_b32 s16, 0
	s_nop 0
	v_writelane_b32 v253, s3, 4
	s_mov_b32 s2, s14
	v_writelane_b32 v253, s2, 5
	s_nop 1
	v_writelane_b32 v253, s3, 6
	s_lshl_b64 s[2:3], s[14:15], 11
	v_writelane_b32 v253, s2, 7
	s_nop 1
	v_writelane_b32 v253, s3, 8
	s_add_u32 s2, s10, 0x73e2100
	s_addc_u32 s3, s11, 0
	v_writelane_b32 v253, s2, 9
	s_nop 1
	v_writelane_b32 v253, s3, 10
	s_add_u32 s2, s10, 0x73e2c00
	s_addc_u32 s3, s11, 0
	v_writelane_b32 v253, s2, 11
	s_nop 1
	v_writelane_b32 v253, s3, 12
	s_mov_b32 s2, 0
	v_writelane_b32 v253, s2, 13
	v_cmp_eq_u32_e64 s[2:3], 0, v1
	s_nop 1
	v_writelane_b32 v253, s2, 14
	s_nop 1
	v_writelane_b32 v253, s3, 15
	v_writelane_b32 v253, s84, 16
	s_mov_b64 s[2:3], 0
	s_nop 0
	v_writelane_b32 v253, s85, 17
	v_writelane_b32 v253, s94, 18
	s_nop 1
	v_writelane_b32 v253, s95, 19
	v_writelane_b32 v253, s68, 20
	s_nop 1
	v_writelane_b32 v253, s69, 21
	s_branch .LBB0_112

; __global__ void __launch_bounds__(512, 2) fwd_megakernel(Params p) {
;     ...
;   if (blockIdx.x == 0 && threadIdx.x < 24) ctr[threadIdx.x] = 0u;
;   if (blockIdx.x == 0 && threadIdx.x == 32) ctr[32] = 0u;
;   grid.sync();
.LBB0_1514:
	v_readlane_b32 s2, v252, 0
	s_nop 3
	s_cmp_lg_u32 s2, 0
	s_cbranch_scc1 .Lfs_end
	s_load_dwordx2 s[4:5], s[0:1], 0x108
	v_mov_b32_e32 v2, 0x2b7c000
	v_mov_b32_e32 v3, 0
	s_waitcnt lgkmcnt(0)
	global_store_dword v2, v3, s[4:5] offset:132 sc0 sc1
	s_waitcnt vmcnt(0)
